# v190 + hand-written P11 re-laid out so every load (dwordx2) and store (dwordx4) instruction is lane-contiguous (512 B / 1 KiB contiguous per instruction)
# speedup vs baseline: 1.0070x; 1.0070x over previous
.LBB0_569:
	s_or_b64 exec, exec, s[0:1]
	s_barrier
	v_and_b32_e32 v0, 63, v212
	v_readfirstlane_b32 s0, v212
	v_lshlrev_b32_e32 v1, 3, v0
	v_lshlrev_b32_e32 v2, 4, v0
	s_lshr_b32 s0, s0, 6
	s_lshl_b32 s0, s0, 3
	s_add_i32 s0, s0, s66
	s_mov_b32 s1, 0
	v_add_u32_e32 v3, 0x1000, v2
	s_lshl_b64 s[2:3], s[0:1], 12
	s_add_u32 s2, s2, s20
	s_addc_u32 s3, s3, s21
	s_lshl_b64 s[4:5], s[0:1], 13
	s_add_u32 s4, s4, s30
	s_addc_u32 s5, s5, s31
	global_load_dwordx4 v[100:103], v2, s[28:29]
	global_load_dwordx4 v[104:107], v2, s[28:29] offset:1024
	global_load_dwordx4 v[108:111], v2, s[28:29] offset:2048
	global_load_dwordx4 v[112:115], v2, s[28:29] offset:3072
	global_load_dwordx4 v[116:119], v3, s[28:29]
	global_load_dwordx4 v[120:123], v3, s[28:29] offset:1024
	global_load_dwordx4 v[124:127], v3, s[28:29] offset:2048
	global_load_dwordx4 v[128:131], v3, s[28:29] offset:3072
	global_load_dwordx2 v[16:17], v1, s[2:3] nt
	global_load_dwordx2 v[18:19], v1, s[2:3] offset:512 nt
	global_load_dwordx2 v[20:21], v1, s[2:3] offset:1024 nt
	global_load_dwordx2 v[22:23], v1, s[2:3] offset:1536 nt
	global_load_dwordx2 v[24:25], v1, s[2:3] offset:2048 nt
	global_load_dwordx2 v[26:27], v1, s[2:3] offset:2560 nt
	global_load_dwordx2 v[28:29], v1, s[2:3] offset:3072 nt
	global_load_dwordx2 v[30:31], v1, s[2:3] offset:3584 nt
	v_xor_b32_e32 v6, 1, v0
	v_xor_b32_e32 v7, 2, v0
	v_xor_b32_e32 v8, 4, v0
	v_xor_b32_e32 v9, 8, v0
	v_xor_b32_e32 v10, 16, v0
	v_xor_b32_e32 v11, 32, v0
	v_lshlrev_b32_e32 v6, 2, v6
	v_lshlrev_b32_e32 v7, 2, v7
	v_lshlrev_b32_e32 v8, 2, v8
	v_lshlrev_b32_e32 v9, 2, v9
	v_lshlrev_b32_e32 v10, 2, v10
	v_lshlrev_b32_e32 v11, 2, v11
	v_mov_b32_e32 v84, 0x358637bd
	s_mov_b32 s6, 0
	s_waitcnt vmcnt(0)
.Lp11_loop:
	s_add_u32 s8, s2, 0x1000
	s_addc_u32 s9, s3, 0
	global_load_dwordx2 v[32:33], v1, s[8:9] nt
	global_load_dwordx2 v[34:35], v1, s[8:9] offset:512 nt
	global_load_dwordx2 v[36:37], v1, s[8:9] offset:1024 nt
	global_load_dwordx2 v[38:39], v1, s[8:9] offset:1536 nt
	global_load_dwordx2 v[40:41], v1, s[8:9] offset:2048 nt
	global_load_dwordx2 v[42:43], v1, s[8:9] offset:2560 nt
	global_load_dwordx2 v[44:45], v1, s[8:9] offset:3072 nt
	global_load_dwordx2 v[46:47], v1, s[8:9] offset:3584 nt
	s_waitcnt vmcnt(16)
	v_lshlrev_b32_e32 v48, 16, v16
	v_and_b32_e32 v49, 0xffff0000, v16
	v_lshlrev_b32_e32 v50, 16, v17
	v_and_b32_e32 v51, 0xffff0000, v17
	v_lshlrev_b32_e32 v52, 16, v18
	v_and_b32_e32 v53, 0xffff0000, v18
	v_lshlrev_b32_e32 v54, 16, v19
	v_and_b32_e32 v55, 0xffff0000, v19
	v_lshlrev_b32_e32 v56, 16, v20
	v_and_b32_e32 v57, 0xffff0000, v20
	v_lshlrev_b32_e32 v58, 16, v21
	v_and_b32_e32 v59, 0xffff0000, v21
	v_lshlrev_b32_e32 v60, 16, v22
	v_and_b32_e32 v61, 0xffff0000, v22
	v_lshlrev_b32_e32 v62, 16, v23
	v_and_b32_e32 v63, 0xffff0000, v23
	v_lshlrev_b32_e32 v64, 16, v24
	v_and_b32_e32 v65, 0xffff0000, v24
	v_lshlrev_b32_e32 v66, 16, v25
	v_and_b32_e32 v67, 0xffff0000, v25
	v_lshlrev_b32_e32 v68, 16, v26
	v_and_b32_e32 v69, 0xffff0000, v26
	v_lshlrev_b32_e32 v70, 16, v27
	v_and_b32_e32 v71, 0xffff0000, v27
	v_lshlrev_b32_e32 v72, 16, v28
	v_and_b32_e32 v73, 0xffff0000, v28
	v_lshlrev_b32_e32 v74, 16, v29
	v_and_b32_e32 v75, 0xffff0000, v29
	v_lshlrev_b32_e32 v76, 16, v30
	v_and_b32_e32 v77, 0xffff0000, v30
	v_lshlrev_b32_e32 v78, 16, v31
	v_and_b32_e32 v79, 0xffff0000, v31
	v_pk_mul_f32 v[80:81], v[48:49], v[48:49]
	v_pk_fma_f32 v[80:81], v[50:51], v[50:51], v[80:81]
	v_pk_fma_f32 v[80:81], v[52:53], v[52:53], v[80:81]
	v_pk_fma_f32 v[80:81], v[54:55], v[54:55], v[80:81]
	v_pk_fma_f32 v[80:81], v[56:57], v[56:57], v[80:81]
	v_pk_fma_f32 v[80:81], v[58:59], v[58:59], v[80:81]
	v_pk_fma_f32 v[80:81], v[60:61], v[60:61], v[80:81]
	v_pk_fma_f32 v[80:81], v[62:63], v[62:63], v[80:81]
	v_pk_fma_f32 v[80:81], v[64:65], v[64:65], v[80:81]
	v_pk_fma_f32 v[80:81], v[66:67], v[66:67], v[80:81]
	v_pk_fma_f32 v[80:81], v[68:69], v[68:69], v[80:81]
	v_pk_fma_f32 v[80:81], v[70:71], v[70:71], v[80:81]
	v_pk_fma_f32 v[80:81], v[72:73], v[72:73], v[80:81]
	v_pk_fma_f32 v[80:81], v[74:75], v[74:75], v[80:81]
	v_pk_fma_f32 v[80:81], v[76:77], v[76:77], v[80:81]
	v_pk_fma_f32 v[80:81], v[78:79], v[78:79], v[80:81]
	v_add_f32_e32 v82, v80, v81
	ds_bpermute_b32 v83, v6, v82
	s_waitcnt lgkmcnt(0)
	v_add_f32_e32 v82, v82, v83
	ds_bpermute_b32 v83, v7, v82
	s_waitcnt lgkmcnt(0)
	v_add_f32_e32 v82, v82, v83
	ds_bpermute_b32 v83, v8, v82
	s_waitcnt lgkmcnt(0)
	v_add_f32_e32 v82, v82, v83
	ds_bpermute_b32 v83, v9, v82
	s_waitcnt lgkmcnt(0)
	v_add_f32_e32 v82, v82, v83
	ds_bpermute_b32 v83, v10, v82
	s_waitcnt lgkmcnt(0)
	v_add_f32_e32 v82, v82, v83
	ds_bpermute_b32 v83, v11, v82
	s_waitcnt lgkmcnt(0)
	v_add_f32_e32 v82, v82, v83
	v_fmamk_f32 v82, v82, 0x3a000000, v84
	v_rsq_f32_e32 v82, v82
	s_nop 0
	v_mov_b32_e32 v83, v82
	v_pk_mul_f32 v[48:49], v[48:49], v[82:83]
	v_pk_mul_f32 v[50:51], v[50:51], v[82:83]
	v_pk_mul_f32 v[52:53], v[52:53], v[82:83]
	v_pk_mul_f32 v[54:55], v[54:55], v[82:83]
	v_pk_mul_f32 v[56:57], v[56:57], v[82:83]
	v_pk_mul_f32 v[58:59], v[58:59], v[82:83]
	v_pk_mul_f32 v[60:61], v[60:61], v[82:83]
	v_pk_mul_f32 v[62:63], v[62:63], v[82:83]
	v_pk_mul_f32 v[64:65], v[64:65], v[82:83]
	v_pk_mul_f32 v[66:67], v[66:67], v[82:83]
	v_pk_mul_f32 v[68:69], v[68:69], v[82:83]
	v_pk_mul_f32 v[70:71], v[70:71], v[82:83]
	v_pk_mul_f32 v[72:73], v[72:73], v[82:83]
	v_pk_mul_f32 v[74:75], v[74:75], v[82:83]
	v_pk_mul_f32 v[76:77], v[76:77], v[82:83]
	v_pk_mul_f32 v[78:79], v[78:79], v[82:83]
	v_pk_mul_f32 v[48:49], v[48:49], v[100:101]
	v_pk_mul_f32 v[50:51], v[50:51], v[102:103]
	v_pk_mul_f32 v[52:53], v[52:53], v[104:105]
	v_pk_mul_f32 v[54:55], v[54:55], v[106:107]
	v_pk_mul_f32 v[56:57], v[56:57], v[108:109]
	v_pk_mul_f32 v[58:59], v[58:59], v[110:111]
	v_pk_mul_f32 v[60:61], v[60:61], v[112:113]
	v_pk_mul_f32 v[62:63], v[62:63], v[114:115]
	v_pk_mul_f32 v[64:65], v[64:65], v[116:117]
	v_pk_mul_f32 v[66:67], v[66:67], v[118:119]
	v_pk_mul_f32 v[68:69], v[68:69], v[120:121]
	v_pk_mul_f32 v[70:71], v[70:71], v[122:123]
	v_pk_mul_f32 v[72:73], v[72:73], v[124:125]
	v_pk_mul_f32 v[74:75], v[74:75], v[126:127]
	v_pk_mul_f32 v[76:77], v[76:77], v[128:129]
	v_pk_mul_f32 v[78:79], v[78:79], v[130:131]
	global_store_dwordx4 v2, v[48:51], s[4:5] nt
	global_store_dwordx4 v2, v[52:55], s[4:5] offset:1024 nt
	global_store_dwordx4 v2, v[56:59], s[4:5] offset:2048 nt
	global_store_dwordx4 v2, v[60:63], s[4:5] offset:3072 nt
	global_store_dwordx4 v3, v[64:67], s[4:5] nt
	global_store_dwordx4 v3, v[68:71], s[4:5] offset:1024 nt
	global_store_dwordx4 v3, v[72:75], s[4:5] offset:2048 nt
	global_store_dwordx4 v3, v[76:79], s[4:5] offset:3072 nt
	s_add_u32 s2, s2, 0x2000
	s_addc_u32 s3, s3, 0
	global_load_dwordx2 v[16:17], v1, s[2:3] nt
	global_load_dwordx2 v[18:19], v1, s[2:3] offset:512 nt
	global_load_dwordx2 v[20:21], v1, s[2:3] offset:1024 nt
	global_load_dwordx2 v[22:23], v1, s[2:3] offset:1536 nt
	global_load_dwordx2 v[24:25], v1, s[2:3] offset:2048 nt
	global_load_dwordx2 v[26:27], v1, s[2:3] offset:2560 nt
	global_load_dwordx2 v[28:29], v1, s[2:3] offset:3072 nt
	global_load_dwordx2 v[30:31], v1, s[2:3] offset:3584 nt
	s_waitcnt vmcnt(16)
	s_add_u32 s10, s4, 0x2000
	s_addc_u32 s11, s5, 0
	v_lshlrev_b32_e32 v48, 16, v32
	v_and_b32_e32 v49, 0xffff0000, v32
	v_lshlrev_b32_e32 v50, 16, v33
	v_and_b32_e32 v51, 0xffff0000, v33
	v_lshlrev_b32_e32 v52, 16, v34
	v_and_b32_e32 v53, 0xffff0000, v34
	v_lshlrev_b32_e32 v54, 16, v35
	v_and_b32_e32 v55, 0xffff0000, v35
	v_lshlrev_b32_e32 v56, 16, v36
	v_and_b32_e32 v57, 0xffff0000, v36
	v_lshlrev_b32_e32 v58, 16, v37
	v_and_b32_e32 v59, 0xffff0000, v37
	v_lshlrev_b32_e32 v60, 16, v38
	v_and_b32_e32 v61, 0xffff0000, v38
	v_lshlrev_b32_e32 v62, 16, v39
	v_and_b32_e32 v63, 0xffff0000, v39
	v_lshlrev_b32_e32 v64, 16, v40
	v_and_b32_e32 v65, 0xffff0000, v40
	v_lshlrev_b32_e32 v66, 16, v41
	v_and_b32_e32 v67, 0xffff0000, v41
	v_lshlrev_b32_e32 v68, 16, v42
	v_and_b32_e32 v69, 0xffff0000, v42
	v_lshlrev_b32_e32 v70, 16, v43
	v_and_b32_e32 v71, 0xffff0000, v43
	v_lshlrev_b32_e32 v72, 16, v44
	v_and_b32_e32 v73, 0xffff0000, v44
	v_lshlrev_b32_e32 v74, 16, v45
	v_and_b32_e32 v75, 0xffff0000, v45
	v_lshlrev_b32_e32 v76, 16, v46
	v_and_b32_e32 v77, 0xffff0000, v46
	v_lshlrev_b32_e32 v78, 16, v47
	v_and_b32_e32 v79, 0xffff0000, v47
	v_pk_mul_f32 v[80:81], v[48:49], v[48:49]
	v_pk_fma_f32 v[80:81], v[50:51], v[50:51], v[80:81]
	v_pk_fma_f32 v[80:81], v[52:53], v[52:53], v[80:81]
	v_pk_fma_f32 v[80:81], v[54:55], v[54:55], v[80:81]
	v_pk_fma_f32 v[80:81], v[56:57], v[56:57], v[80:81]
	v_pk_fma_f32 v[80:81], v[58:59], v[58:59], v[80:81]
	v_pk_fma_f32 v[80:81], v[60:61], v[60:61], v[80:81]
	v_pk_fma_f32 v[80:81], v[62:63], v[62:63], v[80:81]
	v_pk_fma_f32 v[80:81], v[64:65], v[64:65], v[80:81]
	v_pk_fma_f32 v[80:81], v[66:67], v[66:67], v[80:81]
	v_pk_fma_f32 v[80:81], v[68:69], v[68:69], v[80:81]
	v_pk_fma_f32 v[80:81], v[70:71], v[70:71], v[80:81]
	v_pk_fma_f32 v[80:81], v[72:73], v[72:73], v[80:81]
	v_pk_fma_f32 v[80:81], v[74:75], v[74:75], v[80:81]
	v_pk_fma_f32 v[80:81], v[76:77], v[76:77], v[80:81]
	v_pk_fma_f32 v[80:81], v[78:79], v[78:79], v[80:81]
	v_add_f32_e32 v82, v80, v81
	ds_bpermute_b32 v83, v6, v82
	s_waitcnt lgkmcnt(0)
	v_add_f32_e32 v82, v82, v83
	ds_bpermute_b32 v83, v7, v82
	s_waitcnt lgkmcnt(0)
	v_add_f32_e32 v82, v82, v83
	ds_bpermute_b32 v83, v8, v82
	s_waitcnt lgkmcnt(0)
	v_add_f32_e32 v82, v82, v83
	ds_bpermute_b32 v83, v9, v82
	s_waitcnt lgkmcnt(0)
	v_add_f32_e32 v82, v82, v83
	ds_bpermute_b32 v83, v10, v82
	s_waitcnt lgkmcnt(0)
	v_add_f32_e32 v82, v82, v83
	ds_bpermute_b32 v83, v11, v82
	s_waitcnt lgkmcnt(0)
	v_add_f32_e32 v82, v82, v83
	v_fmamk_f32 v82, v82, 0x3a000000, v84
	v_rsq_f32_e32 v82, v82
	s_nop 0
	v_mov_b32_e32 v83, v82
	v_pk_mul_f32 v[48:49], v[48:49], v[82:83]
	v_pk_mul_f32 v[50:51], v[50:51], v[82:83]
	v_pk_mul_f32 v[52:53], v[52:53], v[82:83]
	v_pk_mul_f32 v[54:55], v[54:55], v[82:83]
	v_pk_mul_f32 v[56:57], v[56:57], v[82:83]
	v_pk_mul_f32 v[58:59], v[58:59], v[82:83]
	v_pk_mul_f32 v[60:61], v[60:61], v[82:83]
	v_pk_mul_f32 v[62:63], v[62:63], v[82:83]
	v_pk_mul_f32 v[64:65], v[64:65], v[82:83]
	v_pk_mul_f32 v[66:67], v[66:67], v[82:83]
	v_pk_mul_f32 v[68:69], v[68:69], v[82:83]
	v_pk_mul_f32 v[70:71], v[70:71], v[82:83]
	v_pk_mul_f32 v[72:73], v[72:73], v[82:83]
	v_pk_mul_f32 v[74:75], v[74:75], v[82:83]
	v_pk_mul_f32 v[76:77], v[76:77], v[82:83]
	v_pk_mul_f32 v[78:79], v[78:79], v[82:83]
	v_pk_mul_f32 v[48:49], v[48:49], v[100:101]
	v_pk_mul_f32 v[50:51], v[50:51], v[102:103]
	v_pk_mul_f32 v[52:53], v[52:53], v[104:105]
	v_pk_mul_f32 v[54:55], v[54:55], v[106:107]
	v_pk_mul_f32 v[56:57], v[56:57], v[108:109]
	v_pk_mul_f32 v[58:59], v[58:59], v[110:111]
	v_pk_mul_f32 v[60:61], v[60:61], v[112:113]
	v_pk_mul_f32 v[62:63], v[62:63], v[114:115]
	v_pk_mul_f32 v[64:65], v[64:65], v[116:117]
	v_pk_mul_f32 v[66:67], v[66:67], v[118:119]
	v_pk_mul_f32 v[68:69], v[68:69], v[120:121]
	v_pk_mul_f32 v[70:71], v[70:71], v[122:123]
	v_pk_mul_f32 v[72:73], v[72:73], v[124:125]
	v_pk_mul_f32 v[74:75], v[74:75], v[126:127]
	v_pk_mul_f32 v[76:77], v[76:77], v[128:129]
	v_pk_mul_f32 v[78:79], v[78:79], v[130:131]
	global_store_dwordx4 v2, v[48:51], s[10:11] nt
	global_store_dwordx4 v2, v[52:55], s[10:11] offset:1024 nt
	global_store_dwordx4 v2, v[56:59], s[10:11] offset:2048 nt
	global_store_dwordx4 v2, v[60:63], s[10:11] offset:3072 nt
	global_store_dwordx4 v3, v[64:67], s[10:11] nt
	global_store_dwordx4 v3, v[68:71], s[10:11] offset:1024 nt
	global_store_dwordx4 v3, v[72:75], s[10:11] offset:2048 nt
	global_store_dwordx4 v3, v[76:79], s[10:11] offset:3072 nt
	s_add_u32 s4, s4, 0x4000
	s_addc_u32 s5, s5, 0
	s_add_i32 s6, s6, 2
	s_cmp_lt_u32 s6, 8
	s_cbranch_scc1 .Lp11_loop
	s_endpgm
